# work rebalancing: last 2 k-blocks of w_in moved from the HBM-bound prologue into the slack of the FFN1-gu dedicated converter workgroups
# speedup vs baseline: 1.0075x; 1.0066x over previous
.LBB0_29:
	v_mov_b32_e32 v16, v183
	s_cmpk_gt_i32 s4, 0x314d
	v_readfirstlane_b32 s3, v16
	s_cbranch_scc1 .LBB0_427
	s_cmpk_lt_i32 s4, 0xb00
	s_mov_b32 s5, 1
	s_cbranch_scc1 .LBB0_34
	s_cmpk_gt_u32 s4, 0x15ff
	s_cbranch_scc0 .LBB0_35
	v_readlane_b32 s16, v234, 40
	v_readlane_b32 s22, v234, 46
	v_readlane_b32 s23, v234, 47
	v_readlane_b32 s24, v234, 48
	v_readlane_b32 s25, v234, 49
	s_add_i32 s12, s4, 0xffffea00
	v_readlane_b32 s17, v234, 41
	v_readlane_b32 s18, v234, 42
	v_readlane_b32 s19, v234, 43
	v_readlane_b32 s20, v234, 44
	v_readlane_b32 s21, v234, 45
	v_readlane_b32 s26, v234, 50
	v_readlane_b32 s27, v234, 51
	v_readlane_b32 s28, v234, 52
	v_readlane_b32 s29, v234, 53
	v_readlane_b32 s30, v234, 54
	v_readlane_b32 s31, v234, 55
	s_mov_b64 s[8:9], s[22:23]
	s_mov_b64 s[10:11], s[24:25]
	s_cbranch_execz .LBB0_36
	s_mov_b64 s[6:7], 0x4400000
	s_movk_i32 s28, 0x3a28
	s_mov_b32 s5, 3
	s_branch .LBB0_37

.LBB0_79:
	s_add_i32 s41, s4, s50
	s_cmpk_lt_i32 s41, 0x314e
	s_cselect_b64 s[10:11], -1, 0
	s_cmpk_gt_i32 s41, 0x314d
	s_cselect_b64 s[8:9], -1, 0
	s_and_b64 vcc, exec, s[8:9]
	s_mov_b64 s[12:13], s[6:7]
	s_mov_b32 s42, s28
	s_mov_b32 s43, s5
	s_mov_b32 s44, s2
	s_mov_b32 s45, s29
	s_cbranch_vccnz .LBB0_121
	s_cmpk_lt_i32 s41, 0xb00
	s_cbranch_scc1 .LBB0_84
	s_cmpk_gt_u32 s41, 0x15ff
	s_cbranch_scc0 .LBB0_85
	v_readlane_b32 s12, v234, 40
	v_readlane_b32 s14, v234, 42
	v_readlane_b32 s15, v234, 43
	v_readlane_b32 s16, v234, 44
	v_readlane_b32 s17, v234, 45
	v_readlane_b32 s18, v234, 46
	v_readlane_b32 s19, v234, 47
	v_readlane_b32 s20, v234, 48
	v_readlane_b32 s21, v234, 49
	s_add_i32 s3, s41, 0xffffea00
	v_readlane_b32 s13, v234, 41
	v_readlane_b32 s22, v234, 50
	v_readlane_b32 s23, v234, 51
	v_readlane_b32 s24, v234, 52
	v_readlane_b32 s25, v234, 53
	v_readlane_b32 s26, v234, 54
	v_readlane_b32 s27, v234, 55
	s_mov_b64 s[14:15], s[18:19]
	s_mov_b64 s[16:17], s[20:21]
	s_cbranch_execz .LBB0_86
	s_mov_b64 s[12:13], 0x4400000
	s_movk_i32 s42, 0x3a28
	s_mov_b32 s43, 3
	s_branch .LBB0_87

.LBB0_511:
	v_readlane_b32 s0, v234, 12
	v_writelane_b32 v233, s52, 12
	s_abs_i32 s52, s0
	v_cvt_f32_u32_e32 v0, s52
	s_sub_i32 s0, 0, s52
	v_readlane_b32 s1, v234, 13
	v_writelane_b32 v233, s50, 13
	v_rcp_iflag_f32_e32 v0, v0
	s_nop 0
	v_writelane_b32 v233, s51, 14
	v_mul_f32_e32 v0, 0x4f7ffffe, v0
	v_cvt_u32_f32_e32 v0, v0
	s_nop 0
	v_readfirstlane_b32 s53, v0
	s_mul_i32 s0, s0, s53
	s_mul_hi_u32 s0, s53, s0
	s_add_i32 s53, s53, s0
	s_mul_hi_u32 s0, s53, 0x5ac
	s_mul_i32 s0, s0, s52
	s_sub_i32 s0, 0x5ac, s0
	s_sub_i32 s1, s0, s52
	s_cmp_ge_u32 s0, s52
	s_cselect_b32 s0, s1, s0
	s_sub_i32 s1, s0, s52
	s_cmp_ge_u32 s0, s52
	s_movk_i32 s5, 0xf2
	s_cmp_eq_u32 s5, 0
	s_cselect_b64 s[0:1], -1, 0
	s_cmp_lt_i32 s4, s5
	s_cselect_b64 s[2:3], -1, 0
	s_or_b64 s[0:1], s[0:1], s[2:3]
	s_and_b64 vcc, exec, s[0:1]
	s_cbranch_vccnz .LBB0_931
	v_readlane_b32 s2, v234, 14
	v_readlane_b32 s3, v234, 12
	v_readfirstlane_b32 s0, v183
	s_sub_i32 s2, s2, s5
	s_sub_i32 s3, s3, s5
	s_lshl_b32 s2, s2, 3
	s_lshr_b32 s0, s0, 6
	s_add_i32 s4, s2, s0
	s_lshl_b32 s33, s3, 3
	s_cmp_ge_u32 s4, 0x12ae
	s_cbranch_scc1 .LBB0_931
	v_readlane_b32 s30, v234, 2
	v_readlane_b32 s31, v234, 3
	v_and_b32_e32 v176, 7, v183
	v_bfe_u32 v185, v183, 3, 3
	v_lshlrev_b32_e32 v177, 4, v185
	v_lshlrev_b32_e32 v186, 4, v176
	s_cmp_lt_u32 s4, 0x12ae
	s_cbranch_scc1 .Lcv1_p0_go
	s_mov_b32 s22, 0
	s_branch .Lcv1_p0_end

.Lcv1_p0_seg1:
	s_cmp_lt_u32 s4, 0xcd2
	s_cbranch_scc0 .Lcv1_p0_seg2
	s_add_u32 s34, s4, 0x104e
	s_mul_i32 s39, s34, 18002
	s_lshr_b32 s39, s39, 22
	s_mul_i32 s40, s39, 233
	s_sub_u32 s40, s34, s40
	v_readlane_b32 s0, v234, 48
	v_readlane_b32 s1, v234, 49
	s_mul_i32 s2, s39, 0x3a2800
	s_lshl_b32 s3, s40, 8
	s_add_u32 s2, s2, s3
	s_add_u32 s0, s0, s2
	s_addc_u32 s1, s1, 0
	s_mov_b32 s41, 0xe8a0
	s_mov_b32 s42, 0x74500
	s_lshl_b32 s2, s40, 18
	s_lshl_b32 s3, s39, 7
	s_add_u32 s2, s2, s3
	s_add_u32 s2, s2, 0x43d8000
	s_add_u32 s16, s30, s2
	s_addc_u32 s17, s31, 0
	s_mov_b32 s20, 0x1000
	s_mov_b32 s21, 0x4000
	s_lshl_b32 s23, s40, 6
	s_mov_b64 s[46:47], -1
	s_cmp_eq_u32 s40, 232
	s_cbranch_scc0 .Lcv1_p0_full1
	s_mov_b64 s[46:47], 0xffff

.Lcv1_p0_seg2:
	s_sub_u32 s34, s4, 0xcd2
	s_mul_i32 s39, s34, 5958
	s_lshr_b32 s39, s39, 19
	s_mul_i32 s40, s39, 88
	s_sub_u32 s40, s34, s40
	v_readlane_b32 s0, v234, 4
	v_readlane_b32 s1, v234, 5
	s_mul_i32 s2, s39, 0x160000
	s_lshl_b32 s3, s40, 8
	s_add_u32 s2, s2, s3
	s_add_u32 s0, s0, s2
	s_addc_u32 s1, s1, 0
	s_mov_b32 s41, 0x5800
	s_mov_b32 s42, 0x2c000
	s_lshr_b32 s2, s40, 1
	s_lshl_b32 s2, s2, 8
	s_and_b32 s3, s40, 1
	s_lshl_b32 s3, s3, 6
	s_add_u32 s2, s2, s3
	s_mul_i32 s2, s2, 0x1000
	s_lshl_b32 s3, s39, 7
	s_add_u32 s2, s2, s3
	s_add_u32 s2, s2, 0x8700000
	s_add_u32 s16, s30, s2
	s_addc_u32 s17, s31, 0
	s_mov_b32 s20, 0x1000
	s_mov_b32 s21, 0x4000
	s_mov_b32 s23, -1
	v_readlane_b32 s8, v233, 6
	v_readlane_b32 s9, v233, 7
	s_lshl_b32 s3, s39, 8
	s_mov_b32 s22, 18
	s_nop 0
	s_add_u32 s8, s8, s3
	s_addc_u32 s9, s9, 0

.Lcv1_p0_end:
	s_cmp_lt_u32 s4, 0x12ae
	s_cbranch_scc1 .Lcv1_p1_go
	s_mov_b32 s28, 0
	s_branch .Lcv1_p1_end

.Lcv1_p1_seg1:
	s_cmp_lt_u32 s4, 0xcd2
	s_cbranch_scc0 .Lcv1_p1_seg2
	s_add_u32 s34, s4, 0x104e
	s_mul_i32 s39, s34, 18002
	s_lshr_b32 s39, s39, 22
	s_mul_i32 s40, s39, 233
	s_sub_u32 s40, s34, s40
	v_readlane_b32 s0, v234, 48
	v_readlane_b32 s1, v234, 49
	s_mul_i32 s2, s39, 0x3a2800
	s_lshl_b32 s3, s40, 8
	s_add_u32 s2, s2, s3
	s_add_u32 s0, s0, s2
	s_addc_u32 s1, s1, 0
	s_mov_b32 s41, 0xe8a0
	s_mov_b32 s42, 0x74500
	s_lshl_b32 s2, s40, 18
	s_lshl_b32 s3, s39, 7
	s_add_u32 s2, s2, s3
	s_add_u32 s2, s2, 0x43d8000
	s_add_u32 s24, s30, s2
	s_addc_u32 s25, s31, 0
	s_mov_b32 s26, 0x1000
	s_mov_b32 s27, 0x4000
	s_lshl_b32 s29, s40, 6
	s_mov_b64 s[46:47], -1
	s_cmp_eq_u32 s40, 232
	s_cbranch_scc0 .Lcv1_p1_full1
	s_mov_b64 s[46:47], 0xffff

.Lcv1_p1_seg2:
	s_sub_u32 s34, s4, 0xcd2
	s_mul_i32 s39, s34, 5958
	s_lshr_b32 s39, s39, 19
	s_mul_i32 s40, s39, 88
	s_sub_u32 s40, s34, s40
	v_readlane_b32 s0, v234, 4
	v_readlane_b32 s1, v234, 5
	s_mul_i32 s2, s39, 0x160000
	s_lshl_b32 s3, s40, 8
	s_add_u32 s2, s2, s3
	s_add_u32 s0, s0, s2
	s_addc_u32 s1, s1, 0
	s_mov_b32 s41, 0x5800
	s_mov_b32 s42, 0x2c000
	s_lshr_b32 s2, s40, 1
	s_lshl_b32 s2, s2, 8
	s_and_b32 s3, s40, 1
	s_lshl_b32 s3, s3, 6
	s_add_u32 s2, s2, s3
	s_mul_i32 s2, s2, 0x1000
	s_lshl_b32 s3, s39, 7
	s_add_u32 s2, s2, s3
	s_add_u32 s2, s2, 0x8700000
	s_add_u32 s24, s30, s2
	s_addc_u32 s25, s31, 0
	s_mov_b32 s26, 0x1000
	s_mov_b32 s27, 0x4000
	s_mov_b32 s29, -1
	v_readlane_b32 s8, v233, 6
	v_readlane_b32 s9, v233, 7
	s_lshl_b32 s3, s39, 8
	s_mov_b32 s28, 18
	s_nop 0
	s_add_u32 s8, s8, s3
	s_addc_u32 s9, s9, 0

.Lcv1_pa_plain:
	v_pk_mul_f32 v[0:1], v[0:1], v[128:129] op_sel_hi:[1,0]
	v_pk_mul_f32 v[2:3], v[2:3], v[128:129] op_sel_hi:[1,0]
	v_pk_mul_f32 v[4:5], v[4:5], v[128:129] op_sel_hi:[1,0]
	v_pk_mul_f32 v[6:7], v[6:7], v[128:129] op_sel_hi:[1,0]
	v_pk_mul_f32 v[8:9], v[8:9], v[128:129] op_sel:[0,1]
	v_pk_mul_f32 v[10:11], v[10:11], v[128:129] op_sel:[0,1]
	v_pk_mul_f32 v[12:13], v[12:13], v[128:129] op_sel:[0,1]
	v_pk_mul_f32 v[14:15], v[14:15], v[128:129] op_sel:[0,1]
	v_pk_mul_f32 v[16:17], v[16:17], v[130:131] op_sel_hi:[1,0]
	v_pk_mul_f32 v[18:19], v[18:19], v[130:131] op_sel_hi:[1,0]
	v_pk_mul_f32 v[20:21], v[20:21], v[130:131] op_sel_hi:[1,0]
	v_pk_mul_f32 v[22:23], v[22:23], v[130:131] op_sel_hi:[1,0]
	v_pk_mul_f32 v[24:25], v[24:25], v[130:131] op_sel:[0,1]
	v_pk_mul_f32 v[26:27], v[26:27], v[130:131] op_sel:[0,1]
	v_pk_mul_f32 v[28:29], v[28:29], v[130:131] op_sel:[0,1]
	v_pk_mul_f32 v[30:31], v[30:31], v[130:131] op_sel:[0,1]
	v_pk_mul_f32 v[32:33], v[32:33], v[132:133] op_sel_hi:[1,0]
	v_pk_mul_f32 v[34:35], v[34:35], v[132:133] op_sel_hi:[1,0]
	v_pk_mul_f32 v[36:37], v[36:37], v[132:133] op_sel_hi:[1,0]
	v_pk_mul_f32 v[38:39], v[38:39], v[132:133] op_sel_hi:[1,0]
	v_pk_mul_f32 v[40:41], v[40:41], v[132:133] op_sel:[0,1]
	v_pk_mul_f32 v[42:43], v[42:43], v[132:133] op_sel:[0,1]
	v_pk_mul_f32 v[44:45], v[44:45], v[132:133] op_sel:[0,1]
	v_pk_mul_f32 v[46:47], v[46:47], v[132:133] op_sel:[0,1]
	v_pk_mul_f32 v[48:49], v[48:49], v[134:135] op_sel_hi:[1,0]
	v_pk_mul_f32 v[50:51], v[50:51], v[134:135] op_sel_hi:[1,0]
	v_pk_mul_f32 v[52:53], v[52:53], v[134:135] op_sel_hi:[1,0]
	v_pk_mul_f32 v[54:55], v[54:55], v[134:135] op_sel_hi:[1,0]
	v_pk_mul_f32 v[56:57], v[56:57], v[134:135] op_sel:[0,1]
	v_pk_mul_f32 v[58:59], v[58:59], v[134:135] op_sel:[0,1]
	v_pk_mul_f32 v[60:61], v[60:61], v[134:135] op_sel:[0,1]
	v_pk_mul_f32 v[62:63], v[62:63], v[134:135] op_sel:[0,1]
	v_cvt_pk_bf16_f32 v144, v0, v8
	v_cvt_pk_bf16_f32 v145, v16, v24
	v_cvt_pk_bf16_f32 v146, v32, v40
	v_cvt_pk_bf16_f32 v147, v48, v56
	global_store_dwordx4 v179, v[144:147], s[16:17]
	v_cvt_pk_bf16_f32 v148, v1, v9
	v_cvt_pk_bf16_f32 v149, v17, v25
	v_cvt_pk_bf16_f32 v150, v33, v41
	v_cvt_pk_bf16_f32 v151, v49, v57
	s_add_u32 s16, s16, s20
	s_addc_u32 s17, s17, 0
	global_store_dwordx4 v179, v[148:151], s[16:17]
	v_cvt_pk_bf16_f32 v152, v2, v10
	v_cvt_pk_bf16_f32 v153, v18, v26
	v_cvt_pk_bf16_f32 v154, v34, v42
	v_cvt_pk_bf16_f32 v155, v50, v58
	s_add_u32 s16, s16, s20
	s_addc_u32 s17, s17, 0
	global_store_dwordx4 v179, v[152:155], s[16:17]
	v_cvt_pk_bf16_f32 v156, v3, v11
	v_cvt_pk_bf16_f32 v157, v19, v27
	v_cvt_pk_bf16_f32 v158, v35, v43
	v_cvt_pk_bf16_f32 v159, v51, v59
	s_add_u32 s16, s16, s20
	s_addc_u32 s17, s17, 0
	global_store_dwordx4 v179, v[156:159], s[16:17]
	s_mov_b64 exec, s[48:49]
	v_cvt_pk_bf16_f32 v160, v4, v12
	v_cvt_pk_bf16_f32 v161, v20, v28
	v_cvt_pk_bf16_f32 v162, v36, v44
	v_cvt_pk_bf16_f32 v163, v52, v60
	s_mul_i32 s2, s20, 29
	s_add_u32 s16, s16, s2
	s_addc_u32 s17, s17, 0
	global_store_dwordx4 v184, v[160:163], s[16:17]
	v_cvt_pk_bf16_f32 v164, v5, v13
	v_cvt_pk_bf16_f32 v165, v21, v29
	v_cvt_pk_bf16_f32 v166, v37, v45
	v_cvt_pk_bf16_f32 v167, v53, v61
	s_add_u32 s16, s16, s20
	s_addc_u32 s17, s17, 0
	global_store_dwordx4 v184, v[164:167], s[16:17]
	v_cvt_pk_bf16_f32 v168, v6, v14
	v_cvt_pk_bf16_f32 v169, v22, v30
	v_cvt_pk_bf16_f32 v170, v38, v46
	v_cvt_pk_bf16_f32 v171, v54, v62
	s_add_u32 s16, s16, s20
	s_addc_u32 s17, s17, 0
	global_store_dwordx4 v184, v[168:171], s[16:17]
	v_cvt_pk_bf16_f32 v172, v7, v15
	v_cvt_pk_bf16_f32 v173, v23, v31
	v_cvt_pk_bf16_f32 v174, v39, v47
	v_cvt_pk_bf16_f32 v175, v55, v63
	s_add_u32 s16, s16, s20
	s_addc_u32 s17, s17, 0
	global_store_dwordx4 v184, v[172:175], s[16:17]
	s_mov_b64 exec, -1
	s_cmp_lt_u32 s4, 0x12ae
	s_cbranch_scc1 .Lcv1_la_go
	s_mov_b32 s22, 0
	s_branch .Lcv1_la_end

.Lcv1_pb_plain:
	v_pk_mul_f32 v[64:65], v[64:65], v[136:137] op_sel_hi:[1,0]
	v_pk_mul_f32 v[66:67], v[66:67], v[136:137] op_sel_hi:[1,0]
	v_pk_mul_f32 v[68:69], v[68:69], v[136:137] op_sel_hi:[1,0]
	v_pk_mul_f32 v[70:71], v[70:71], v[136:137] op_sel_hi:[1,0]
	v_pk_mul_f32 v[72:73], v[72:73], v[136:137] op_sel:[0,1]
	v_pk_mul_f32 v[74:75], v[74:75], v[136:137] op_sel:[0,1]
	v_pk_mul_f32 v[76:77], v[76:77], v[136:137] op_sel:[0,1]
	v_pk_mul_f32 v[78:79], v[78:79], v[136:137] op_sel:[0,1]
	v_pk_mul_f32 v[80:81], v[80:81], v[138:139] op_sel_hi:[1,0]
	v_pk_mul_f32 v[82:83], v[82:83], v[138:139] op_sel_hi:[1,0]
	v_pk_mul_f32 v[84:85], v[84:85], v[138:139] op_sel_hi:[1,0]
	v_pk_mul_f32 v[86:87], v[86:87], v[138:139] op_sel_hi:[1,0]
	v_pk_mul_f32 v[88:89], v[88:89], v[138:139] op_sel:[0,1]
	v_pk_mul_f32 v[90:91], v[90:91], v[138:139] op_sel:[0,1]
	v_pk_mul_f32 v[92:93], v[92:93], v[138:139] op_sel:[0,1]
	v_pk_mul_f32 v[94:95], v[94:95], v[138:139] op_sel:[0,1]
	v_pk_mul_f32 v[96:97], v[96:97], v[140:141] op_sel_hi:[1,0]
	v_pk_mul_f32 v[98:99], v[98:99], v[140:141] op_sel_hi:[1,0]
	v_pk_mul_f32 v[100:101], v[100:101], v[140:141] op_sel_hi:[1,0]
	v_pk_mul_f32 v[102:103], v[102:103], v[140:141] op_sel_hi:[1,0]
	v_pk_mul_f32 v[104:105], v[104:105], v[140:141] op_sel:[0,1]
	v_pk_mul_f32 v[106:107], v[106:107], v[140:141] op_sel:[0,1]
	v_pk_mul_f32 v[108:109], v[108:109], v[140:141] op_sel:[0,1]
	v_pk_mul_f32 v[110:111], v[110:111], v[140:141] op_sel:[0,1]
	v_pk_mul_f32 v[112:113], v[112:113], v[142:143] op_sel_hi:[1,0]
	v_pk_mul_f32 v[114:115], v[114:115], v[142:143] op_sel_hi:[1,0]
	v_pk_mul_f32 v[116:117], v[116:117], v[142:143] op_sel_hi:[1,0]
	v_pk_mul_f32 v[118:119], v[118:119], v[142:143] op_sel_hi:[1,0]
	v_pk_mul_f32 v[120:121], v[120:121], v[142:143] op_sel:[0,1]
	v_pk_mul_f32 v[122:123], v[122:123], v[142:143] op_sel:[0,1]
	v_pk_mul_f32 v[124:125], v[124:125], v[142:143] op_sel:[0,1]
	v_pk_mul_f32 v[126:127], v[126:127], v[142:143] op_sel:[0,1]
	v_cvt_pk_bf16_f32 v144, v64, v72
	v_cvt_pk_bf16_f32 v145, v80, v88
	v_cvt_pk_bf16_f32 v146, v96, v104
	v_cvt_pk_bf16_f32 v147, v112, v120
	global_store_dwordx4 v179, v[144:147], s[24:25]
	v_cvt_pk_bf16_f32 v148, v65, v73
	v_cvt_pk_bf16_f32 v149, v81, v89
	v_cvt_pk_bf16_f32 v150, v97, v105
	v_cvt_pk_bf16_f32 v151, v113, v121
	s_add_u32 s24, s24, s26
	s_addc_u32 s25, s25, 0
	global_store_dwordx4 v179, v[148:151], s[24:25]
	v_cvt_pk_bf16_f32 v152, v66, v74
	v_cvt_pk_bf16_f32 v153, v82, v90
	v_cvt_pk_bf16_f32 v154, v98, v106
	v_cvt_pk_bf16_f32 v155, v114, v122
	s_add_u32 s24, s24, s26
	s_addc_u32 s25, s25, 0
	global_store_dwordx4 v179, v[152:155], s[24:25]
	v_cvt_pk_bf16_f32 v156, v67, v75
	v_cvt_pk_bf16_f32 v157, v83, v91
	v_cvt_pk_bf16_f32 v158, v99, v107
	v_cvt_pk_bf16_f32 v159, v115, v123
	s_add_u32 s24, s24, s26
	s_addc_u32 s25, s25, 0
	global_store_dwordx4 v179, v[156:159], s[24:25]
	s_mov_b64 exec, s[48:49]
	v_cvt_pk_bf16_f32 v160, v68, v76
	v_cvt_pk_bf16_f32 v161, v84, v92
	v_cvt_pk_bf16_f32 v162, v100, v108
	v_cvt_pk_bf16_f32 v163, v116, v124
	s_mul_i32 s2, s26, 29
	s_add_u32 s24, s24, s2
	s_addc_u32 s25, s25, 0
	global_store_dwordx4 v184, v[160:163], s[24:25]
	v_cvt_pk_bf16_f32 v164, v69, v77
	v_cvt_pk_bf16_f32 v165, v85, v93
	v_cvt_pk_bf16_f32 v166, v101, v109
	v_cvt_pk_bf16_f32 v167, v117, v125
	s_add_u32 s24, s24, s26
	s_addc_u32 s25, s25, 0
	global_store_dwordx4 v184, v[164:167], s[24:25]
	v_cvt_pk_bf16_f32 v168, v70, v78
	v_cvt_pk_bf16_f32 v169, v86, v94
	v_cvt_pk_bf16_f32 v170, v102, v110
	v_cvt_pk_bf16_f32 v171, v118, v126
	s_add_u32 s24, s24, s26
	s_addc_u32 s25, s25, 0
	global_store_dwordx4 v184, v[168:171], s[24:25]
	v_cvt_pk_bf16_f32 v172, v71, v79
	v_cvt_pk_bf16_f32 v173, v87, v95
	v_cvt_pk_bf16_f32 v174, v103, v111
	v_cvt_pk_bf16_f32 v175, v119, v127
	s_add_u32 s24, s24, s26
	s_addc_u32 s25, s25, 0
	global_store_dwordx4 v184, v[172:175], s[24:25]
	s_mov_b64 exec, -1
	s_cmp_lt_u32 s4, 0x12ae
	s_cbranch_scc1 .Lcv1_lb_go
	s_mov_b32 s28, 0
	s_branch .Lcv1_lb_end
